# mixer item rotation: wave's k-th prompt item shifted by k so each wave gets three different task types (balances per-wave time)
# baseline (speedup 1.0000x reference)
.LBB0_232:
	v_readlane_b32 s0, v235, 45
	s_cmpk_eq_i32 s18, 0x77f
	s_cselect_b32 s0, 1, 0x781
	s_cmpk_eq_i32 s18, 0xeff
	s_cselect_b32 s0, 1, s0
	s_add_i32 s18, s18, s0
	v_readlane_b32 s0, v235, 46
	s_cmp_lt_i32 s18, s0
	s_cbranch_scc1 .LBB0_233
	s_cmpk_eq_i32 s0, 0x1400
	s_cbranch_scc0 ATH0_DONE
	s_sub_u32 s0, s2, 176
	s_cmp_lt_u32 s0, 32
	s_cbranch_scc0 .LBB0_307
	v_readlane_b32 s1, v235, 20
	s_cmp_eq_u32 s1, 0
	s_cbranch_scc0 .LBB0_307
	s_add_i32 s18, s0, 0x1480
	v_mov_b32_e32 v236, 0x3700
	s_movk_i32 s1, 0x2000

.LBB0_940:
	s_cmpk_eq_i32 s26, 0x77f
	s_cselect_b32 s0, 1, 0x781
	s_cmpk_eq_i32 s26, 0xeff
	s_cselect_b32 s0, 1, s0
	s_add_i32 s26, s26, s0
	v_readlane_b32 s0, v235, 46
	s_cmp_lt_i32 s26, s0
	s_cbranch_scc1 .LBB0_941
	s_cmpk_eq_i32 s0, 0x1400
	s_cbranch_scc0 ATH1_DONE
	s_sub_u32 s0, s2, 176
	s_cmp_lt_u32 s0, 32
	s_cbranch_scc0 .LBB0_1015
	v_readlane_b32 s1, v235, 20
	s_cmp_eq_u32 s1, 0
	s_cbranch_scc0 .LBB0_1015
	s_add_i32 s26, s0, 0x1480
	v_mov_b32_e32 v236, 0x3800
	s_movk_i32 s1, 0x2000

.LBB0_1649:
	s_cmpk_eq_i32 s30, 0x77f
	s_cselect_b32 s0, 1, 0x781
	s_cmpk_eq_i32 s30, 0xeff
	s_cselect_b32 s0, 1, s0
	s_add_i32 s30, s30, s0
	v_readlane_b32 s0, v235, 46
	s_cmp_lt_i32 s30, s0
	s_cbranch_scc1 .LBB0_1650
	s_cmpk_eq_i32 s0, 0x1400
	s_cbranch_scc0 ATH2_DONE
	s_sub_u32 s0, s2, 176
	s_cmp_lt_u32 s0, 32
	s_cbranch_scc0 .LBB0_1724
	v_readlane_b32 s1, v235, 20
	s_cmp_eq_u32 s1, 0
	s_cbranch_scc0 .LBB0_1724
	s_add_i32 s30, s0, 0x1480
	v_mov_b32_e32 v236, 0x3900
	s_movk_i32 s1, 0x2000

.LBB0_2358:
	s_cmpk_eq_i32 s30, 0x77f
	s_cselect_b32 s0, 1, 0x781
	s_cmpk_eq_i32 s30, 0xeff
	s_cselect_b32 s0, 1, s0
	s_add_i32 s30, s30, s0
	v_readlane_b32 s0, v235, 46
	s_cmp_lt_i32 s30, s0
	s_cbranch_scc1 .LBB0_2359
	s_cmpk_eq_i32 s0, 0x1400
	s_cbranch_scc0 ATH3_DONE
	s_sub_u32 s0, s2, 176
	s_cmp_lt_u32 s0, 32
	s_cbranch_scc0 .LBB0_2433
	v_readlane_b32 s1, v235, 20
	s_cmp_eq_u32 s1, 0
	s_cbranch_scc0 .LBB0_2433
	s_add_i32 s30, s0, 0x1480
	v_mov_b32_e32 v236, 0x3a00
	s_movk_i32 s1, 0x2000
